# attention: softmax scale folded into the q-latent norm (8C) + MFMA block scale 2^-3 on Q, QK accumulators start from the running offset (no per-element fma), 4 K operand buffers
# speedup vs baseline: 1.0082x; 1.0082x over previous
; __device__ __forceinline__ int ltid() { int t = threadIdx.x; asm volatile("" : "+v"(t)); return t; }
; #define SLOAD(i, k0) do { sr_[i].vs = *(const u32x4*)(vsrc + (k0)); \
;     { const unsigned char* kt_ = Kh + (size_t)(k0) * 192; sr_[i].ks0 = *(const u32x4*)(kt_ + tid * 16); if (k2) sr_[i].ks1 = *(const u32x4*)(kt_ + 8192 + tid * 16); } } while (0)
; __device__ __forceinline__ void attn_body(const unsigned char* __restrict__ Qb, const unsigned char* __restrict__ Kh, const unsigned char* __restrict__ Vt,
;                                           bf16_t* __restrict__ Ob, int seq, char* lds) {
;   const int tid = ltid(), wid = tid >> 6, lane = tid & 63, r32 = lane & 31, hi = lane >> 5;
;   unsigned char* V_lds = (unsigned char*)lds; unsigned char* K_lds = (unsigned char*)(lds + 3 * SHM_V);
;   float* ws = (float*)(lds + 3 * SHM_V + 3 * SHM_K) + wid * 64; float* li_l = ws; float* al_l = ws + 32;
;   float m_reg = -1e30f, l_reg = 0; f32x16 o[4] = {}; i32x8 qr[3];
;   const unsigned char* Qw = Qb + (long)(wid * QBLK + r32) * 192 + hi * 32;
; #pragma unroll
;   for (int m = 0; m < 3; ++m) { const u32x4 a0 = *reinterpret_cast<const u32x4*>(Qw + m * 64), a1 = *reinterpret_cast<const u32x4*>(Qw + m * 64 + 16);
;     qr[m] = (i32x8){(int)a0.x, (int)a0.y, (int)a0.z, (int)a0.w, (int)a1.x, (int)a1.y, (int)a1.z, (int)a1.w}; }
;   const unsigned char* vsrc = Vt + (size_t)(tid >> 2) * S_ + (tid & 3) * 16;
;   const int vw = (tid >> 2) * 80 + ((tid & 3) >> 1) * 16 + (tid & 1) * 8;
;   const int kw0 = KSWZ(tid / 12, (tid % 12) * 16), kw1 = KSWZ((tid + 512) / 12, ((tid + 512) % 12) * 16);
;   const bool k2 = tid < 256;
;   struct { u32x4 vs, ks0, ks1; } sr_[SDEPTH];
;     ...
;   f32x16 pA0, pA1, pB0, pB1; float mnA, mnB, alA, alB; i32x8 pa; const int NT = seq / KVBLK;
;     ...
;   int sP = 0, sC = 1, sN = 2;
;   SLOAD(0, 0); asm volatile("s_waitcnt vmcnt(0)" ::: "memory"); SWRITE(0, 0); SLOAD(0, KVBLK); __syncthreads();
;   asm volatile("s_waitcnt vmcnt(0)" ::: "memory"); SWRITE(1, 0); if (2 < NT) SLOAD(0, 2 * KVBLK);
;   qkt(pA0, pA1, K_lds, qr, r32, hi); partialSM(pA0, pA1, m_reg, mnA, alA);
.Latt_p1b:
	s_add_u32 s8, s8, 0x3000
	s_addc_u32 s9, s9, 0
	s_add_u32 s10, s10, 64
	s_addc_u32 s11, s11, 0
	v_mul_u32_u24_e32 v217, 0x50, v225
	v_lshrrev_b32_e32 v230, 1, v228
	v_lshl_add_u32 v217, v230, 4, v217
	v_and_b32_e32 v230, 1, v192
	v_lshl_add_u32 v217, v230, 3, v217
	s_mov_b32 s0, 0x2aaaaaab
	v_mul_hi_u32 v230, v192, s0
	v_lshrrev_b32_e32 v230, 1, v230
	v_add_lshl_u32 v218, v230, v192, 4
	v_add_u32_e32 v226, 0x200, v192
	v_mul_hi_u32 v230, v226, s0
	v_lshrrev_b32_e32 v230, 1, v230
	v_add_lshl_u32 v219, v230, v226, 4
	v_mul_u32_u24_e32 v220, 0xd0, v201
	v_lshl_add_u32 v220, v229, 5, v220
	v_mul_u32_u24_e32 v221, 0x50, v201
	v_lshl_add_u32 v221, v229, 5, v221
	v_lshlrev_b32_e32 v222, 8, v231
	v_add_u32_e32 v222, 0x17000, v222
	v_lshl_add_u32 v223, v229, 4, v222
	v_lshl_add_u32 v222, v201, 2, v222
	v_mov_b64_e32 v[0:1], 0
	v_mov_b64_e32 v[2:3], 0
	v_mov_b64_e32 v[4:5], 0
	v_mov_b64_e32 v[6:7], 0
	v_mov_b64_e32 v[8:9], 0
	v_mov_b64_e32 v[10:11], 0
	v_mov_b64_e32 v[12:13], 0
	v_mov_b64_e32 v[14:15], 0
	v_mov_b64_e32 v[16:17], 0
	v_mov_b64_e32 v[18:19], 0
	v_mov_b64_e32 v[20:21], 0
	v_mov_b64_e32 v[22:23], 0
	v_mov_b64_e32 v[24:25], 0
	v_mov_b64_e32 v[26:27], 0
	v_mov_b64_e32 v[28:29], 0
	v_mov_b64_e32 v[30:31], 0
	v_mov_b64_e32 v[32:33], 0
	v_mov_b64_e32 v[34:35], 0
	v_mov_b64_e32 v[36:37], 0
	v_mov_b64_e32 v[38:39], 0
	v_mov_b64_e32 v[40:41], 0
	v_mov_b64_e32 v[42:43], 0
	v_mov_b64_e32 v[44:45], 0
	v_mov_b64_e32 v[46:47], 0
	v_mov_b64_e32 v[48:49], 0
	v_mov_b64_e32 v[50:51], 0
	v_mov_b64_e32 v[52:53], 0
	v_mov_b64_e32 v[54:55], 0
	v_mov_b64_e32 v[56:57], 0
	v_mov_b64_e32 v[58:59], 0
	v_mov_b64_e32 v[60:61], 0
	v_mov_b64_e32 v[62:63], 0
	v_mov_b32_e32 v193, 0xf149f2ca
	v_mov_b32_e32 v194, 0
	s_mov_b32 s13, 0x40fc551e
	v_mov_b64_e32 v[160:161], 0
	v_mov_b64_e32 v[162:163], 0
	v_mov_b64_e32 v[164:165], 0
	v_mov_b64_e32 v[166:167], 0
	v_mov_b64_e32 v[168:169], 0
	v_mov_b64_e32 v[170:171], 0
	v_mov_b64_e32 v[172:173], 0
	v_mov_b64_e32 v[174:175], 0
	v_mov_b32_e32 v227, 0
	v_mov_b32_e32 v201, 0x7c7c7c7c
	s_waitcnt vmcnt(0)
	ds_write2_b32 v217, v202, v204 offset1:1
	ds_write2_b32 v217, v203, v205 offset0:8 offset1:9
	ds_write_b128 v218, v[206:209] offset:40960
	s_cmp_lt_u32 s12, 4
	s_cbranch_scc0 .Latt_p2
	v_add_u32_e32 v231, 0, v219
	ds_write_b128 v231, v[210:213] offset:40960

; __device__ __forceinline__ int ltid() { int t = threadIdx.x; asm volatile("" : "+v"(t)); return t; }
; __device__ __forceinline__ void qkt(f32x16& p0, f32x16& p1, const unsigned char* Ks, const i32x8* qr, int r32, int hi) {
;   p0 = f32x16{}; p1 = f32x16{};
; #pragma unroll
;   for (int m = 0; m < 3; ++m) { const int cb = m * 64 + hi * 32;
;     const u32x4 a0 = *reinterpret_cast<const u32x4*>(Ks + KSWZ(r32, cb)), a1 = *reinterpret_cast<const u32x4*>(Ks + KSWZ(r32, cb) + 16);
;     const u32x4 c0 = *reinterpret_cast<const u32x4*>(Ks + KSWZ(32 + r32, cb)), c1 = *reinterpret_cast<const u32x4*>(Ks + KSWZ(32 + r32, cb) + 16);
;     const i32x8 b0 = {(int)a0.x, (int)a0.y, (int)a0.z, (int)a0.w, (int)a1.x, (int)a1.y, (int)a1.z, (int)a1.w};
;     const i32x8 b1 = {(int)c0.x, (int)c0.y, (int)c0.z, (int)c0.w, (int)c1.x, (int)c1.y, (int)c1.z, (int)c1.w};
;     p0 = __builtin_amdgcn_mfma_scale_f32_32x32x64_f8f6f4(b0, qr[m], p0, 0, 0, 0, 0x7F7F7F7F, 0, 0x7F7F7F7F);
;     p1 = __builtin_amdgcn_mfma_scale_f32_32x32x64_f8f6f4(b1, qr[m], p1, 0, 0, 0, 0x7F7F7F7F, 0, 0x7F7F7F7F); }
; }
; __device__ __forceinline__ void pv_d0(f32x16* o, const unsigned char* Vs, const i32x8& pa, int r32, int hi) {
; #pragma unroll
;   for (int d0 = 0; d0 < 4; ++d0) { const unsigned char* vp = Vs + (32 * d0 + r32) * 80 + hi * 32;
;     const u32x4 a0 = *reinterpret_cast<const u32x4*>(vp), a1 = *reinterpret_cast<const u32x4*>(vp + 16);
;     const i32x8 vb = {(int)a0.x, (int)a0.y, (int)a0.z, (int)a0.w, (int)a1.x, (int)a1.y, (int)a1.z, (int)a1.w};
;     o[d0] = __builtin_amdgcn_mfma_scale_f32_32x32x64_f8f6f4(pa, vb, o[d0], 0, 0, 0, 0x7A7A7A7A, 0, 0x7F7F7F7F); }
; }
; __device__ __forceinline__ void attn_body(const unsigned char* __restrict__ Qb, const unsigned char* __restrict__ Kh, const unsigned char* __restrict__ Vt,
;                                           bf16_t* __restrict__ Ob, int seq, char* lds) {
;   const int tid = ltid(), wid = tid >> 6, lane = tid & 63, r32 = lane & 31, hi = lane >> 5;
;   unsigned char* V_lds = (unsigned char*)lds; unsigned char* K_lds = (unsigned char*)(lds + 3 * SHM_V);
;   float* ws = (float*)(lds + 3 * SHM_V + 3 * SHM_K) + wid * 64; float* li_l = ws; float* al_l = ws + 32;
;   float m_reg = -1e30f, l_reg = 0; f32x16 o[4] = {}; i32x8 qr[3];
;   const unsigned char* Qw = Qb + (long)(wid * QBLK + r32) * 192 + hi * 32;
; #pragma unroll
.Latt_p5:
	v_mov_b32_e32 v202, v140
	v_mov_b32_e32 v203, v141
	v_mov_b32_e32 v204, v142
	v_mov_b32_e32 v205, v143
	v_mov_b32_e32 v206, v144
	v_mov_b32_e32 v207, v145
	v_mov_b32_e32 v208, v146
	v_mov_b32_e32 v209, v147
	v_mov_b32_e32 v210, v148
	v_mov_b32_e32 v211, v149
	v_mov_b32_e32 v212, v150
	v_mov_b32_e32 v213, v151
	s_waitcnt lgkmcnt(0)
	s_barrier
	ds_read_b128 v[128:131], v220 offset:40960
	ds_read_b128 v[132:135], v220 offset:40976
	ds_read_b128 v[136:139], v220 offset:47616
	ds_read_b128 v[140:143], v220 offset:47632
	ds_read_b128 v[144:147], v220 offset:41024
	ds_read_b128 v[148:151], v220 offset:41040
	ds_read_b128 v[152:155], v220 offset:47680
	ds_read_b128 v[156:159], v220 offset:47696
	s_mov_b32 s6, 0
.Latt_loop:
	s_setprio 0
	s_and_b32 s0, s6, 3
	s_mul_i32 s0, s0, 13312
	v_add_u32_e32 v229, s0, v220
	s_add_u32 s0, s6, 1
	s_and_b32 s0, s0, 3
	s_mul_i32 s0, s0, 13312
	v_add_u32_e32 v225, s0, v220
	s_cmp_eq_u32 s6, 0
	s_cbranch_scc1 .Latt_m_first
	s_add_u32 s0, s6, 3
	s_and_b32 s0, s0, 3
	s_mul_i32 s0, s0, 10240
	v_add_u32_e32 v224, s0, v221
	ds_read_b128 v[176:179], v224 offset:0
	ds_read_b128 v[180:183], v224 offset:16
	ds_read_b128 v[184:187], v224 offset:2560
	ds_read_b128 v[188:191], v224 offset:2576
	s_waitcnt lgkmcnt(4)
	v_mfma_scale_f32_32x32x64_f8f6f4 v[64:79], v[128:135], v[96:103], v[160:175], v235, v201 op_sel_hi:[0,0,0]
	ds_read_b128 v[128:131], v229 offset:41088
	ds_read_b128 v[132:135], v229 offset:41104
	v_mfma_scale_f32_32x32x64_f8f6f4 v[80:95], v[136:143], v[96:103], v[160:175], v235, v201 op_sel_hi:[0,0,0]
	ds_read_b128 v[136:139], v229 offset:47744
	ds_read_b128 v[140:143], v229 offset:47760
	v_mfma_scale_f32_32x32x64_f8f6f4 v[64:79], v[144:151], v[104:111], v[64:79], v235, v201 op_sel_hi:[0,0,0]
	ds_read_b128 v[144:147], v225 offset:41024
	ds_read_b128 v[148:151], v225 offset:41040
	v_mfma_scale_f32_32x32x64_f8f6f4 v[80:95], v[152:159], v[104:111], v[80:95], v235, v201 op_sel_hi:[0,0,0]
	ds_read_b128 v[152:155], v225 offset:47680
	ds_read_b128 v[156:159], v225 offset:47696
	s_waitcnt lgkmcnt(6)
	v_mfma_scale_f32_32x32x64_f8f6f4 v[64:79], v[128:135], v[112:119], v[64:79], v235, v201 op_sel_hi:[0,0,0]
	ds_read_b128 v[128:131], v225 offset:40960
	ds_read_b128 v[132:135], v225 offset:40976
	s_waitcnt lgkmcnt(6)
	v_mfma_scale_f32_32x32x64_f8f6f4 v[80:95], v[136:143], v[112:119], v[80:95], v235, v201 op_sel_hi:[0,0,0]
	ds_read_b128 v[136:139], v225 offset:47616
	ds_read_b128 v[140:143], v225 offset:47632
	s_waitcnt lgkmcnt(8)
	v_mfma_scale_f32_32x32x64_f8f6f4 v[0:15], v[120:127], v[176:183], v[0:15], v237, v235 op_sel_hi:[0,0,0]
	ds_read_b128 v[176:179], v224 offset:5120
	ds_read_b128 v[180:183], v224 offset:5136
	v_mfma_scale_f32_32x32x64_f8f6f4 v[16:31], v[120:127], v[184:191], v[16:31], v237, v235 op_sel_hi:[0,0,0]
	ds_read_b128 v[184:187], v224 offset:7680
	ds_read_b128 v[188:191], v224 offset:7696
	s_waitcnt lgkmcnt(2)
	v_mfma_scale_f32_32x32x64_f8f6f4 v[32:47], v[120:127], v[176:183], v[32:47], v237, v235 op_sel_hi:[0,0,0]
	s_waitcnt lgkmcnt(0)
	v_mfma_scale_f32_32x32x64_f8f6f4 v[48:63], v[120:127], v[184:191], v[48:63], v237, v235 op_sel_hi:[0,0,0]
	s_add_u32 s4, s6, 2
	s_cmp_lt_u32 s4, 128
	s_cbranch_scc0 .Latt_ms_nowr
	s_and_b32 s0, s4, 3
	s_mul_i32 s1, s0, 10240
	s_mul_i32 s0, s0, 13312
	v_add_u32_e32 v224, s1, v217
	v_add_u32_e32 v225, s0, v218
	s_waitcnt vmcnt(0)
	ds_write2_b32 v224, v202, v204 offset1:1
	ds_write2_b32 v224, v203, v205 offset0:8 offset1:9
	ds_write_b128 v225, v[206:209] offset:40960
	s_cmp_lt_u32 s12, 4
	s_cbranch_scc0 .Latt_ms_w1
	v_add_u32_e32 v231, s0, v219
	ds_write_b128 v231, v[210:213] offset:40960

; __device__ __forceinline__ void qkt(f32x16& p0, f32x16& p1, const unsigned char* Ks, const i32x8* qr, int r32, int hi) {
;   p0 = f32x16{}; p1 = f32x16{};
; #pragma unroll
;   for (int m = 0; m < 3; ++m) { const int cb = m * 64 + hi * 32;
;     const u32x4 a0 = *reinterpret_cast<const u32x4*>(Ks + KSWZ(r32, cb)), a1 = *reinterpret_cast<const u32x4*>(Ks + KSWZ(r32, cb) + 16);
;     const u32x4 c0 = *reinterpret_cast<const u32x4*>(Ks + KSWZ(32 + r32, cb)), c1 = *reinterpret_cast<const u32x4*>(Ks + KSWZ(32 + r32, cb) + 16);
;     const i32x8 b0 = {(int)a0.x, (int)a0.y, (int)a0.z, (int)a0.w, (int)a1.x, (int)a1.y, (int)a1.z, (int)a1.w};
;     const i32x8 b1 = {(int)c0.x, (int)c0.y, (int)c0.z, (int)c0.w, (int)c1.x, (int)c1.y, (int)c1.z, (int)c1.w};
;     p0 = __builtin_amdgcn_mfma_scale_f32_32x32x64_f8f6f4(b0, qr[m], p0, 0, 0, 0, 0x7F7F7F7F, 0, 0x7F7F7F7F);
;     p1 = __builtin_amdgcn_mfma_scale_f32_32x32x64_f8f6f4(b1, qr[m], p1, 0, 0, 0, 0x7F7F7F7F, 0, 0x7F7F7F7F); }
; }
.Latt_m_first:
	s_waitcnt lgkmcnt(0)
	v_mfma_scale_f32_32x32x64_f8f6f4 v[64:79], v[128:135], v[96:103], v[160:175], v235, v201 op_sel_hi:[0,0,0]
	ds_read_b128 v[128:131], v229 offset:41088
	ds_read_b128 v[132:135], v229 offset:41104
	v_mfma_scale_f32_32x32x64_f8f6f4 v[80:95], v[136:143], v[96:103], v[160:175], v235, v201 op_sel_hi:[0,0,0]
	ds_read_b128 v[136:139], v229 offset:47744
	ds_read_b128 v[140:143], v229 offset:47760
	v_mfma_scale_f32_32x32x64_f8f6f4 v[64:79], v[144:151], v[104:111], v[64:79], v235, v201 op_sel_hi:[0,0,0]
	ds_read_b128 v[144:147], v225 offset:41024
	ds_read_b128 v[148:151], v225 offset:41040
	v_mfma_scale_f32_32x32x64_f8f6f4 v[80:95], v[152:159], v[104:111], v[80:95], v235, v201 op_sel_hi:[0,0,0]
	ds_read_b128 v[152:155], v225 offset:47680
	ds_read_b128 v[156:159], v225 offset:47696
	s_waitcnt lgkmcnt(6)
	v_mfma_scale_f32_32x32x64_f8f6f4 v[64:79], v[128:135], v[112:119], v[64:79], v235, v201 op_sel_hi:[0,0,0]
	ds_read_b128 v[128:131], v225 offset:40960
	ds_read_b128 v[132:135], v225 offset:40976
	s_waitcnt lgkmcnt(6)
	v_mfma_scale_f32_32x32x64_f8f6f4 v[80:95], v[136:143], v[112:119], v[80:95], v235, v201 op_sel_hi:[0,0,0]
	ds_read_b128 v[136:139], v225 offset:47616
	ds_read_b128 v[140:143], v225 offset:47632
	s_add_u32 s4, s6, 2
	s_cmp_lt_u32 s4, 128
	s_cbranch_scc0 .Latt_mf_nowr
	s_and_b32 s0, s4, 3
	s_mul_i32 s1, s0, 10240
	s_mul_i32 s0, s0, 13312
	v_add_u32_e32 v224, s1, v217
	v_add_u32_e32 v225, s0, v218
	s_waitcnt vmcnt(0)
	ds_write2_b32 v224, v202, v204 offset1:1
	ds_write2_b32 v224, v203, v205 offset0:8 offset1:9
	ds_write_b128 v225, v[206:209] offset:40960
	s_cmp_lt_u32 s12, 4
	s_cbranch_scc0 .Latt_mf_w1
	v_add_u32_e32 v231, s0, v219
	ds_write_b128 v231, v[210:213] offset:40960

; __device__ __forceinline__ void partialSM(f32x16& p0, f32x16& p1, float& m_reg, float& mn, float& alpha) {
;   constexpr float C = SCALE * 1.4426950408889634f;
;   float pmax = p0[0]; for (int r = 1; r < 16; ++r) pmax = fmaxf(pmax, p0[r]); for (int r = 0; r < 16; ++r) pmax = fmaxf(pmax, p1[r]);
;   { auto rr = __builtin_amdgcn_permlane32_swap(__float_as_uint(pmax), __float_as_uint(pmax), false, false);
;     pmax = fmaxf(__uint_as_float(rr[0]), __uint_as_float(rr[1])); }
;   if (__builtin_expect(__all(pmax - m_reg <= THR / SCALE), 1)) { mn = m_reg; alpha = 1.f; }
;   else { mn = fmaxf(m_reg, pmax); alpha = __builtin_amdgcn_exp2f((m_reg - mn) * C); m_reg = mn; }
;   float mnC = -mn * C + 5.f;
;   for (int r = 0; r < 16; ++r) p0[r] = fmaf(p0[r], C, mnC); for (int r = 0; r < 16; ++r) p1[r] = fmaf(p1[r], C, mnC);
;   for (int r = 0; r < 16; ++r) p0[r] = __builtin_amdgcn_exp2f(p0[r]);
; }
; __device__ __forceinline__ void finishSM(f32x16& p0, f32x16& p1, float alpha, float& l_reg, i32x8& pa) {
;   for (int r = 0; r < 16; ++r) p1[r] = __builtin_amdgcn_exp2f(p1[r]);
;   float ps = 0; for (int r = 0; r < 16; ++r) ps += p0[r]; for (int r = 0; r < 16; ++r) ps += p1[r];
;   { auto rr = __builtin_amdgcn_permlane32_swap(__float_as_uint(ps), __float_as_uint(ps), false, false);
;     ps = __uint_as_float(rr[0]) + __uint_as_float(rr[1]); }
;   l_reg = l_reg * alpha + ps;
; #pragma unroll
;   for (int i = 0; i < 4; ++i) { int w0 = 0, w1 = 0;
;     w0 = __builtin_amdgcn_cvt_pk_fp8_f32(p0[4 * i], p0[4 * i + 1], w0, false); w0 = __builtin_amdgcn_cvt_pk_fp8_f32(p0[4 * i + 2], p0[4 * i + 3], w0, true);
;     w1 = __builtin_amdgcn_cvt_pk_fp8_f32(p1[4 * i], p1[4 * i + 1], w1, false); w1 = __builtin_amdgcn_cvt_pk_fp8_f32(p1[4 * i + 2], p1[4 * i + 3], w1, true);
;     pa[i] = w0; pa[4 + i] = w1; }
; }
.Latt_m_nobar:
	s_setprio 0
	v_max3_f32 v228, v64, v65, v66
	v_max3_f32 v229, v80, v81, v82
	v_max3_f32 v228, v228, v67, v68
	v_max3_f32 v229, v229, v83, v84
	v_max3_f32 v228, v228, v69, v70
	v_max3_f32 v229, v229, v85, v86
	v_max3_f32 v228, v228, v71, v72
	v_max3_f32 v229, v229, v87, v88
	v_max3_f32 v228, v228, v73, v74
	v_max3_f32 v229, v229, v89, v90
	v_max3_f32 v228, v228, v75, v76
	v_max3_f32 v229, v229, v91, v92
	v_max3_f32 v228, v228, v77, v78
	v_max3_f32 v229, v229, v93, v94
	v_max3_f32 v228, v228, v79, v95
	v_max_f32_e32 v228, v228, v229
	v_mov_b32_e32 v229, v228
	s_nop 1
	v_permlane32_swap_b32_e32 v228, v229
	v_max_f32_e32 v228, v228, v229
	v_cmp_ge_f32_e32 vcc, s13, v228
	v_mov_b32_e32 v226, 1.0
	s_cmp_eq_u32 s6, 0
	s_cbranch_scc1 .Latt_rare
	s_cmp_eq_u64 vcc, exec
	s_cbranch_scc0 .Latt_rare
.Latt_rare_back:
	v_exp_f32_e32 v64, v64
	v_exp_f32_e32 v65, v65
	v_exp_f32_e32 v66, v66
	v_exp_f32_e32 v67, v67
	v_add_f32_e32 v230, v64, v65
	v_exp_f32_e32 v68, v68
	v_add_f32_e32 v230, v66, v230
	v_exp_f32_e32 v69, v69
	v_cvt_pk_fp8_f32 v120, v64, v65
	v_add_f32_e32 v230, v67, v230
	v_exp_f32_e32 v70, v70
	v_add_f32_e32 v230, v68, v230
	v_exp_f32_e32 v71, v71
	v_cvt_pk_fp8_f32 v120, v66, v67 op_sel:[0,0,1]
	v_add_f32_e32 v230, v69, v230
	v_exp_f32_e32 v72, v72
	v_add_f32_e32 v230, v70, v230
	v_exp_f32_e32 v73, v73
	v_cvt_pk_fp8_f32 v121, v68, v69
	v_add_f32_e32 v230, v71, v230
	v_exp_f32_e32 v74, v74
	v_add_f32_e32 v230, v72, v230
	v_exp_f32_e32 v75, v75
	v_cvt_pk_fp8_f32 v121, v70, v71 op_sel:[0,0,1]
	v_add_f32_e32 v230, v73, v230
	v_exp_f32_e32 v76, v76
	v_add_f32_e32 v230, v74, v230
	v_exp_f32_e32 v77, v77
	v_cvt_pk_fp8_f32 v122, v72, v73
	v_add_f32_e32 v230, v75, v230
	v_exp_f32_e32 v78, v78
	v_add_f32_e32 v230, v76, v230
	v_exp_f32_e32 v79, v79
	v_cvt_pk_fp8_f32 v122, v74, v75 op_sel:[0,0,1]
	v_add_f32_e32 v230, v77, v230
	v_exp_f32_e32 v80, v80
	v_add_f32_e32 v230, v78, v230
	v_exp_f32_e32 v81, v81
	v_cvt_pk_fp8_f32 v123, v76, v77
	v_add_f32_e32 v230, v79, v230
	v_exp_f32_e32 v82, v82
	v_add_f32_e32 v230, v80, v230
	v_exp_f32_e32 v83, v83
	v_cvt_pk_fp8_f32 v123, v78, v79 op_sel:[0,0,1]
	v_add_f32_e32 v230, v81, v230
	v_exp_f32_e32 v84, v84
	v_add_f32_e32 v230, v82, v230
	v_exp_f32_e32 v85, v85
	v_cvt_pk_fp8_f32 v124, v80, v81
	v_add_f32_e32 v230, v83, v230
	v_exp_f32_e32 v86, v86
	v_add_f32_e32 v230, v84, v230
	v_exp_f32_e32 v87, v87
	v_cvt_pk_fp8_f32 v124, v82, v83 op_sel:[0,0,1]
	v_add_f32_e32 v230, v85, v230
	v_exp_f32_e32 v88, v88
	v_add_f32_e32 v230, v86, v230
	v_exp_f32_e32 v89, v89
	v_cvt_pk_fp8_f32 v125, v84, v85
	v_add_f32_e32 v230, v87, v230
	v_exp_f32_e32 v90, v90
	v_add_f32_e32 v230, v88, v230
	v_exp_f32_e32 v91, v91
	v_cvt_pk_fp8_f32 v125, v86, v87 op_sel:[0,0,1]
	v_add_f32_e32 v230, v89, v230
	v_exp_f32_e32 v92, v92
	v_add_f32_e32 v230, v90, v230
	v_exp_f32_e32 v93, v93
	v_cvt_pk_fp8_f32 v126, v88, v89
	v_add_f32_e32 v230, v91, v230
	v_exp_f32_e32 v94, v94
	v_add_f32_e32 v230, v92, v230
	v_exp_f32_e32 v95, v95
	v_cvt_pk_fp8_f32 v126, v90, v91 op_sel:[0,0,1]
	v_add_f32_e32 v230, v93, v230
	v_add_f32_e32 v230, v94, v230
	v_cvt_pk_fp8_f32 v127, v92, v93
	v_add_f32_e32 v230, v95, v230
	v_cvt_pk_fp8_f32 v127, v94, v95 op_sel:[0,0,1]
	v_mov_b32_e32 v229, v230
	s_nop 1
	v_permlane32_swap_b32_e32 v230, v229
	v_add_f32_e32 v230, v230, v229
	v_fma_f32 v194, v194, v226, v230
	s_waitcnt lgkmcnt(0)
	s_cmp_eq_u32 s7, 0
	s_cbranch_scc0 .Latt_v_nobar
	s_barrier

; __device__ __forceinline__ void partialSM(f32x16& p0, f32x16& p1, float& m_reg, float& mn, float& alpha) {
;     ...
;   if (__builtin_expect(__all(pmax - m_reg <= THR / SCALE), 1)) { mn = m_reg; alpha = 1.f; }
;   else { mn = fmaxf(m_reg, pmax); alpha = __builtin_amdgcn_exp2f((m_reg - mn) * C); m_reg = mn; }
.Latt_rare:
	v_sub_f32_e32 v229, v228, v227
	v_max_f32_e32 v229, v193, v229
	v_sub_f32_e32 v231, v193, v229
	v_exp_f32_e32 v226, v231
	v_mov_b32_e32 v193, v229
	v_sub_f32_e32 v231, v236, v229
	v_sub_f32_e32 v229, v231, v227
	v_mov_b32_e32 v227, v231
	v_add_f32_e32 v64, v64, v229
	v_add_f32_e32 v65, v65, v229
	v_add_f32_e32 v66, v66, v229
	v_add_f32_e32 v67, v67, v229
	v_add_f32_e32 v68, v68, v229
	v_add_f32_e32 v69, v69, v229
	v_add_f32_e32 v70, v70, v229
	v_add_f32_e32 v71, v71, v229
	v_add_f32_e32 v72, v72, v229
	v_add_f32_e32 v73, v73, v229
	v_add_f32_e32 v74, v74, v229
	v_add_f32_e32 v75, v75, v229
	v_add_f32_e32 v76, v76, v229
	v_add_f32_e32 v77, v77, v229
	v_add_f32_e32 v78, v78, v229
	v_add_f32_e32 v79, v79, v229
	v_add_f32_e32 v80, v80, v229
	v_add_f32_e32 v81, v81, v229
	v_add_f32_e32 v82, v82, v229
	v_add_f32_e32 v83, v83, v229
	v_add_f32_e32 v84, v84, v229
	v_add_f32_e32 v85, v85, v229
	v_add_f32_e32 v86, v86, v229
	v_add_f32_e32 v87, v87, v229
	v_add_f32_e32 v88, v88, v229
	v_add_f32_e32 v89, v89, v229
	v_add_f32_e32 v90, v90, v229
	v_add_f32_e32 v91, v91, v229
	v_add_f32_e32 v92, v92, v229
	v_add_f32_e32 v93, v93, v229
	v_add_f32_e32 v94, v94, v229
	v_add_f32_e32 v95, v95, v229
	v_mov_b32_e32 v160, v227
	v_mov_b32_e32 v161, v227
	v_mov_b32_e32 v162, v227
	v_mov_b32_e32 v163, v227
	v_mov_b32_e32 v164, v227
	v_mov_b32_e32 v165, v227
	v_mov_b32_e32 v166, v227
	v_mov_b32_e32 v167, v227
	v_mov_b32_e32 v168, v227
	v_mov_b32_e32 v169, v227
	v_mov_b32_e32 v170, v227
	v_mov_b32_e32 v171, v227
	v_mov_b32_e32 v172, v227
	v_mov_b32_e32 v173, v227
	v_mov_b32_e32 v174, v227
	v_mov_b32_e32 v175, v227
	s_mov_b32 exec_hi, 0
	ds_write_b32 v222, v226 offset:128
	s_mov_b64 exec, -1
	s_waitcnt lgkmcnt(0)
	ds_read_b128 v[176:179], v223 offset:128
	ds_read_b128 v[180:183], v223 offset:160
	ds_read_b128 v[184:187], v223 offset:192
	ds_read_b128 v[188:191], v223 offset:224
	s_waitcnt lgkmcnt(0)
	v_mul_f32_e32 v0, v0, v176
	v_mul_f32_e32 v1, v1, v177
	v_mul_f32_e32 v2, v2, v178
	v_mul_f32_e32 v3, v3, v179
	v_mul_f32_e32 v4, v4, v180
	v_mul_f32_e32 v5, v5, v181
	v_mul_f32_e32 v6, v6, v182
	v_mul_f32_e32 v7, v7, v183
	v_mul_f32_e32 v8, v8, v184
	v_mul_f32_e32 v9, v9, v185
	v_mul_f32_e32 v10, v10, v186
	v_mul_f32_e32 v11, v11, v187
	v_mul_f32_e32 v12, v12, v188
	v_mul_f32_e32 v13, v13, v189
	v_mul_f32_e32 v14, v14, v190
	v_mul_f32_e32 v15, v15, v191
	v_mul_f32_e32 v16, v16, v176
	v_mul_f32_e32 v17, v17, v177
	v_mul_f32_e32 v18, v18, v178
	v_mul_f32_e32 v19, v19, v179
	v_mul_f32_e32 v20, v20, v180
	v_mul_f32_e32 v21, v21, v181
	v_mul_f32_e32 v22, v22, v182
	v_mul_f32_e32 v23, v23, v183
	v_mul_f32_e32 v24, v24, v184
	v_mul_f32_e32 v25, v25, v185
	v_mul_f32_e32 v26, v26, v186
	v_mul_f32_e32 v27, v27, v187
	v_mul_f32_e32 v28, v28, v188
	v_mul_f32_e32 v29, v29, v189
	v_mul_f32_e32 v30, v30, v190
	v_mul_f32_e32 v31, v31, v191
	v_mul_f32_e32 v32, v32, v176
	v_mul_f32_e32 v33, v33, v177
	v_mul_f32_e32 v34, v34, v178
	v_mul_f32_e32 v35, v35, v179
	v_mul_f32_e32 v36, v36, v180
	v_mul_f32_e32 v37, v37, v181
	v_mul_f32_e32 v38, v38, v182
	v_mul_f32_e32 v39, v39, v183
	v_mul_f32_e32 v40, v40, v184
	v_mul_f32_e32 v41, v41, v185
	v_mul_f32_e32 v42, v42, v186
	v_mul_f32_e32 v43, v43, v187
	v_mul_f32_e32 v44, v44, v188
	v_mul_f32_e32 v45, v45, v189
	v_mul_f32_e32 v46, v46, v190
	v_mul_f32_e32 v47, v47, v191
	v_mul_f32_e32 v48, v48, v176
	v_mul_f32_e32 v49, v49, v177
	v_mul_f32_e32 v50, v50, v178
	v_mul_f32_e32 v51, v51, v179
	v_mul_f32_e32 v52, v52, v180
	v_mul_f32_e32 v53, v53, v181
	v_mul_f32_e32 v54, v54, v182
	v_mul_f32_e32 v55, v55, v183
	v_mul_f32_e32 v56, v56, v184
	v_mul_f32_e32 v57, v57, v185
	v_mul_f32_e32 v58, v58, v186
	v_mul_f32_e32 v59, v59, v187
	v_mul_f32_e32 v60, v60, v188
	v_mul_f32_e32 v61, v61, v189
	v_mul_f32_e32 v62, v62, v190
	v_mul_f32_e32 v63, v63, v191
	s_branch .Latt_rare_back

; __device__ __forceinline__ void prep_phase(const Params& p, const Bufs& B, int l) {
;     ...
;     for (int s = lbid() * 8 + wid; s < S_; s += gridDim.x * 8) {
;         const bf16_t* pr = B.PROJ + (size_t)s * NPROJP;
;         const u32x4 z4 = (u32x4){0u, 0u, 0u, 0u};
;         u32x4 cm[2], cc[2], cp[2];
; #pragma unroll
;         for (int hf = 0; hf < 2; ++hf) { const int c0 = lane * 16 + hf * 8;
;             cm[hf] = s > 0 ? *(const u32x4*)(pr - NPROJP + c0) : z4; cc[hf] = *(const u32x4*)(pr + c0); cp[hf] = s < S_ - 1 ? *(const u32x4*)(pr + NPROJP + c0) : z4; }
;         const int tensor = lane >> 5, head = (lane & 31) >> 3, j0 = (lane & 7) * 4, base = PC_RQ + tensor * 256 + head * 64;
;         const u32x2 w1 = *(const u32x2*)(pr + base + j0), w2 = *(const u32x2*)(pr + base + 32 + j0);
;         const f32x4 rc4 = *(const f32x4*)(B.RC + (size_t)s * 32 + j0), rs4 = *(const f32x4*)(B.RS + (size_t)s * 32 + j0);
;         const u32x4 cqv = *(const u32x4*)(pr + PC_CQ + lane * 8); const u32x2 ckvv = *(const u32x2*)(pr + PC_CKV + lane * 4);
;         const int l32 = lane & 31, l16 = lane & 15;
;         const bf16_t kr1 = pr[PC_KR + l32], kr2 = pr[PC_KR + 32 + l32]; const float krc = B.RC[(size_t)s * 32 + l32], krs = B.RS[(size_t)s * 32 + l32];
;         const bf16_t gt = pr[PC_GATE + l16]; const float bgl = bg[l16];
; #pragma unroll
;         for (int hf = 0; hf < 2; ++hf) { const int c0 = lane * 16 + hf * 8; float xm[8], x0[8], xp[8], r[8];
;             unpack8(cm[hf], xm); unpack8(cc[hf], x0); unpack8(cp[hf], xp);
; #pragma unroll
;             for (int i = 0; i < 8; ++i) { const float v = xm[i] * wconv[c0 + i] + x0[i] * wconv[1024 + c0 + i] + xp[i] * wconv[2048 + c0 + i]; r[i] = v * __builtin_amdgcn_rcpf(1.f + __expf(-v)); }
;             *(u32x4*)(B.QKML + (size_t)s * 1024 + c0) = pack8(r); }
;         { const float x1[4] = {bflo(w1.x), bfhi(w1.x), bflo(w1.y), bfhi(w1.y)}, x2[4] = {bflo(w2.x), bfhi(w2.x), bflo(w2.y), bfhi(w2.y)};
;             const float sc = tensor ? 0.125f : 1.f; float o1[4], o2[4];
; #pragma unroll
;             for (int i = 0; i < 4; ++i) { o1[i] = (x1[i] * rc4[i] - x2[i] * rs4[i]) * sc; o2[i] = (x2[i] * rc4[i] + x1[i] * rs4[i]) * sc; }
;             u32x2 a, b2; a.x = cvt_pk_bf16(o1[0], o1[1]); a.y = cvt_pk_bf16(o1[2], o1[3]); b2.x = cvt_pk_bf16(o2[0], o2[1]); b2.y = cvt_pk_bf16(o2[2], o2[3]);
.LBB0_496:
	s_or_b64 exec, exec, s[14:15]
	v_mov_b32_e32 v97, v195
	v_lshl_add_u64 v[0:1], v[36:37], 0, v[96:97]
	v_mov_b32_e32 v99, v195
	v_lshl_add_u64 v[0:1], v[0:1], 0, v[98:99]
	v_ashrrev_i32_e32 v57, 31, v56
	v_add_co_u32_e32 v0, vcc, 0x1000, v0
	v_lshlrev_b64 v[38:39], 7, v[56:57]
	s_nop 0
	v_addc_co_u32_e32 v1, vcc, 0, v1, vcc
	flat_load_dwordx2 v[108:109], v[0:1] offset:32
	flat_load_dwordx2 v[110:111], v[0:1] offset:96
	v_lshl_add_u64 v[0:1], v[74:75], 0, v[38:39]
	flat_load_dwordx4 v[4:7], v[0:1]
	v_lshl_add_u64 v[0:1], v[76:77], 0, v[38:39]
	v_mov_b32_e32 v101, v195
	flat_load_dwordx4 v[8:11], v[0:1]
	v_lshl_add_u64 v[0:1], v[36:37], 0, v[100:101]
	s_movk_i32 s1, 0x1000
	v_add_co_u32_e32 v0, vcc, s1, v0
	v_mov_b32_e32 v103, v195
	s_nop 0
	v_addc_co_u32_e32 v1, vcc, 0, v1, vcc
	v_lshl_add_u64 v[40:41], v[36:37], 0, v[102:103]
	s_movk_i32 s0, 0x2000
	v_add_co_u32_e32 v40, vcc, s0, v40
	v_lshlrev_b32_e32 v194, 1, v60
	s_nop 0
	v_addc_co_u32_e32 v41, vcc, 0, v41, vcc
	flat_load_dwordx4 v[0:3], v[0:1] offset:3104
	v_mov_b32_e32 v105, v195
	flat_load_dwordx2 v[106:107], v[40:41] offset:32
	v_lshl_add_u64 v[40:41], v[36:37], 0, v[194:195]
	v_add_co_u32_e32 v40, vcc, s0, v40
	v_lshl_add_u64 v[36:37], v[36:37], 0, v[104:105]
	s_nop 0
	v_addc_co_u32_e32 v41, vcc, 0, v41, vcc
	v_lshl_or_b32 v38, v60, 2, v38
	v_add_co_u32_e32 v36, vcc, s1, v36
	flat_load_ushort v97, v[40:41] offset:544
	flat_load_ushort v99, v[40:41] offset:608
	v_lshl_add_u64 v[40:41], s[2:3], 0, v[38:39]
	v_lshl_add_u64 v[38:39], s[10:11], 0, v[38:39]
	v_addc_co_u32_e32 v37, vcc, 0, v37, vcc
	flat_load_dword v101, v[40:41]
	flat_load_dword v103, v[38:39]
	flat_load_ushort v59, v[36:37]
	global_load_dword v67, v[62:63], off
	s_waitcnt vmcnt(0) lgkmcnt(0)
	v_lshlrev_b32_e32 v119, 16, v32
	v_and_b32_e32 v124, 0xffff0000, v32
	v_lshlrev_b32_e32 v118, 16, v33
	v_and_b32_e32 v117, 0xffff0000, v33
	v_lshlrev_b32_e32 v116, 16, v34
	v_and_b32_e32 v115, 0xffff0000, v34
	v_lshlrev_b32_e32 v114, 16, v35
	v_and_b32_e32 v105, 0xffff0000, v35
	global_load_dwordx4 v[32:35], v[68:69], off offset:16
	global_load_dwordx4 v[48:51], v[68:69], off
	global_load_dwordx4 v[36:39], v[78:79], off offset:16
	global_load_dwordx4 v[44:47], v[78:79], off
	global_load_dwordx4 v[40:43], v[80:81], off offset:16
	global_load_dwordx4 v[52:55], v[80:81], off
	v_lshlrev_b32_e32 v121, 16, v20
	v_lshlrev_b32_e32 v120, 16, v24
	v_lshlrev_b64 v[112:113], 11, v[56:57]
	s_waitcnt vmcnt(4)
	v_mov_b32_e32 v122, v48
	s_waitcnt vmcnt(0)
	v_mov_b32_e32 v123, v52
	v_pk_mul_f32 v[120:121], v[122:123], v[120:121]
	v_mov_b32_e32 v52, v49
	v_fma_f32 v44, v44, v119, v120
	v_add_f32_e32 v44, v44, v121
	v_mul_f32_e32 v48, 0xbfb8aa3b, v44
	v_exp_f32_e32 v48, v48
	v_and_b32_e32 v121, 0xffff0000, v20
	v_and_b32_e32 v120, 0xffff0000, v24
	v_add_f32_e32 v48, 1.0, v48
	v_rcp_f32_e32 v48, v48
	s_nop 0
	v_mul_f32_e32 v119, v44, v48
	v_pk_mul_f32 v[48:49], v[52:53], v[120:121]
	v_lshlrev_b32_e32 v44, 16, v25
	v_fma_f32 v20, v45, v124, v48
	v_add_f32_e32 v20, v20, v49
	v_mul_f32_e32 v24, 0xbfb8aa3b, v20
	v_exp_f32_e32 v24, v24
	v_lshlrev_b32_e32 v45, 16, v21
	v_mov_b32_e32 v48, v50
	v_mov_b32_e32 v49, v54
	v_add_f32_e32 v24, 1.0, v24
	v_rcp_f32_e32 v24, v24
	v_pk_mul_f32 v[44:45], v[48:49], v[44:45]
	v_and_b32_e32 v21, 0xffff0000, v21
	v_mov_b32_e32 v54, v51
	v_mul_f32_e32 v52, v20, v24
	v_fma_f32 v20, v46, v118, v44
	v_add_f32_e32 v20, v20, v45
	v_mul_f32_e32 v24, 0xbfb8aa3b, v20
	v_exp_f32_e32 v24, v24
	v_lshlrev_b32_e32 v50, 16, v28
	v_and_b32_e32 v51, 0xffff0000, v28
	v_and_b32_e32 v53, 0xffff0000, v29
	v_add_f32_e32 v24, 1.0, v24
	v_rcp_f32_e32 v24, v24
	v_lshlrev_b32_e32 v46, 16, v16
	v_mul_f32_e32 v44, v20, v24
	v_and_b32_e32 v20, 0xffff0000, v25
	v_pk_mul_f32 v[20:21], v[54:55], v[20:21]
	v_mov_b32_e32 v24, v32
	v_fma_f32 v20, v47, v117, v20
	v_add_f32_e32 v20, v20, v21
	v_mul_f32_e32 v21, 0xbfb8aa3b, v20
	v_exp_f32_e32 v21, v21
	v_mov_b32_e32 v25, v40
	v_mov_b32_e32 v40, v33
	v_lshlrev_b32_e32 v54, 16, v30
	v_add_f32_e32 v21, 1.0, v21
	v_rcp_f32_e32 v21, v21
	v_and_b32_e32 v55, 0xffff0000, v30
	v_lshlrev_b32_e32 v47, 16, v12
	v_mul_f32_e32 v45, v20, v21
	v_lshlrev_b32_e32 v21, 16, v22
	v_lshlrev_b32_e32 v20, 16, v26
	v_pk_mul_f32 v[20:21], v[24:25], v[20:21]
	v_mov_b32_e32 v24, v34
	v_fma_f32 v20, v36, v116, v20
	v_add_f32_e32 v20, v20, v21
	v_mul_f32_e32 v21, 0xbfb8aa3b, v20
	v_exp_f32_e32 v21, v21
	v_mov_b32_e32 v25, v42
	v_mov_b32_e32 v42, v35
	v_add_f32_e32 v21, 1.0, v21
	v_rcp_f32_e32 v21, v21
	s_nop 0
	v_mul_f32_e32 v32, v20, v21
	v_and_b32_e32 v21, 0xffff0000, v22
	v_and_b32_e32 v20, 0xffff0000, v26
	v_pk_mul_f32 v[20:21], v[40:41], v[20:21]
	s_nop 0
	v_fma_f32 v20, v37, v115, v20
	v_add_f32_e32 v20, v20, v21
	v_mul_f32_e32 v21, 0xbfb8aa3b, v20
	v_exp_f32_e32 v21, v21
	s_nop 0
	v_add_f32_e32 v21, 1.0, v21
	v_rcp_f32_e32 v21, v21
	s_nop 0
	v_mul_f32_e32 v22, v20, v21
	v_lshlrev_b32_e32 v20, 16, v27
	v_lshlrev_b32_e32 v21, 16, v23
	v_pk_mul_f32 v[20:21], v[24:25], v[20:21]
	s_nop 0
	v_fma_f32 v20, v38, v114, v20
	v_add_f32_e32 v20, v20, v21
	v_mul_f32_e32 v21, 0xbfb8aa3b, v20
	v_exp_f32_e32 v21, v21
	s_nop 0
	v_add_f32_e32 v21, 1.0, v21
	v_rcp_f32_e32 v21, v21
	s_nop 0
	v_mul_f32_e32 v24, v20, v21
	v_and_b32_e32 v21, 0xffff0000, v23
	v_and_b32_e32 v20, 0xffff0000, v27
	v_pk_mul_f32 v[20:21], v[42:43], v[20:21]
	s_nop 0
	v_fma_f32 v20, v39, v105, v20
	v_add_f32_e32 v20, v20, v21
	v_mul_f32_e32 v21, 0xbfb8aa3b, v20
	v_exp_f32_e32 v21, v21
	v_lshlrev_b32_e32 v105, 16, v31
	v_add_f32_e32 v21, 1.0, v21
	v_rcp_f32_e32 v21, v21
	s_nop 0
	v_mul_f32_e32 v23, v20, v21
	v_cvt_pk_bf16_f32 v20, v119, v52
	v_cvt_pk_bf16_f32 v21, v44, v45
	v_cvt_pk_bf16_f32 v22, v32, v22
	v_lshl_add_u64 v[32:33], v[94:95], 0, v[112:113]
	v_cvt_pk_bf16_f32 v23, v24, v23
	flat_store_dwordx4 v[32:33], v[20:23]
	v_lshlrev_b32_e32 v52, 16, v29
	v_and_b32_e32 v112, 0xffff0000, v31
	global_load_dwordx4 v[20:23], v[68:69], off offset:48
	global_load_dwordx4 v[34:37], v[68:69], off offset:32
	global_load_dwordx4 v[24:27], v[90:91], off offset:16
	global_load_dwordx4 v[38:41], v[90:91], off
	global_load_dwordx4 v[28:31], v[92:93], off offset:16
	global_load_dwordx4 v[42:45], v[92:93], off
	s_waitcnt vmcnt(0)
; __device__ __forceinline__ unsigned cvt_pk_bf16(float lo, float hi) { unsigned r; asm volatile("v_cvt_pk_bf16_f32 %0, %1, %2" : "=v"(r) : "v"(lo), "v"(hi)); return r; }
; __device__ __forceinline__ void prep_phase(const Params& p, const Bufs& B, int l) {
;     ...
;         for (int hf = 0; hf < 2; ++hf) { const int c0 = lane * 16 + hf * 8; float xm[8], x0[8], xp[8], r[8];
;             unpack8(cm[hf], xm); unpack8(cc[hf], x0); unpack8(cp[hf], xp);
; #pragma unroll
;             for (int i = 0; i < 8; ++i) { const float v = xm[i] * wconv[c0 + i] + x0[i] * wconv[1024 + c0 + i] + xp[i] * wconv[2048 + c0 + i]; r[i] = v * __builtin_amdgcn_rcpf(1.f + __expf(-v)); }
;             *(u32x4*)(B.QKML + (size_t)s * 1024 + c0) = pack8(r); }
;         { const float x1[4] = {bflo(w1.x), bfhi(w1.x), bflo(w1.y), bfhi(w1.y)}, x2[4] = {bflo(w2.x), bfhi(w2.x), bflo(w2.y), bfhi(w2.y)};
;             const float sc = tensor ? 0.125f : 1.f; float o1[4], o2[4];
; #pragma unroll
;             for (int i = 0; i < 4; ++i) { o1[i] = (x1[i] * rc4[i] - x2[i] * rs4[i]) * sc; o2[i] = (x2[i] * rc4[i] + x1[i] * rs4[i]) * sc; }
;             u32x2 a, b2; a.x = cvt_pk_bf16(o1[0], o1[1]); a.y = cvt_pk_bf16(o1[2], o1[3]); b2.x = cvt_pk_bf16(o2[0], o2[1]); b2.y = cvt_pk_bf16(o2[2], o2[3]);
;             bf16_t* d = B.RQK + (size_t)s * 512 + tensor * 256 + head * 64 + j0; *(u32x2*)d = a; *(u32x2*)(d + 32) = b2; }
;         { float f[8]; unpack8(cqv, f); float g4[4] = {bflo(ckvv.x), bfhi(ckvv.x), bflo(ckvv.y), bfhi(ckvv.y)};
;             float ssq = 0.f, ssk = g4[0] * g4[0] + g4[1] * g4[1] + g4[2] * g4[2] + g4[3] * g4[3];
; #pragma unroll
;             for (int i = 0; i < 8; ++i) ssq += f[i] * f[i];
; #pragma unroll
;             for (int o = 32; o > 0; o >>= 1) { ssq += __shfl_xor(ssq, o); ssk += __shfl_xor(ssk, o); }
;             const float rstd = rsqrtf(ssq * (1.f / 512.f) + EPS_), rstk = rsqrtf(ssk * (1.f / 256.f) + EPS_);
; #pragma unroll
;             for (int i = 0; i < 8; ++i) f[i] = f[i] * rstd * gq[lane * 8 + i];
;             *(u32x4*)(B.CQN + (size_t)s * 512 + lane * 8) = pack8(f);
; #pragma unroll
;             for (int i = 0; i < 4; ++i) g4[i] = g4[i] * rstk * gkv[lane * 4 + i];
;             u32x2 o; o.x = cvt_pk_bf16(g4[0], g4[1]); o.y = cvt_pk_bf16(g4[2], g4[3]); *(u32x2*)(B.CKVN + (size_t)s * 256 + lane * 4) = o; }
	v_mov_b32_e32 v48, v34
	v_mov_b32_e32 v49, v42
	v_pk_mul_f32 v[46:47], v[48:49], v[46:47]
	v_mov_b32_e32 v42, v35
	v_fma_f32 v34, v38, v50, v46
	v_add_f32_e32 v34, v34, v47
	v_mul_f32_e32 v38, 0xbfb8aa3b, v34
	v_exp_f32_e32 v38, v38
	v_and_b32_e32 v47, 0xffff0000, v12
	v_and_b32_e32 v46, 0xffff0000, v16
	v_add_f32_e32 v38, 1.0, v38
	v_rcp_f32_e32 v38, v38
	s_nop 0
	v_mul_f32_e32 v48, v34, v38
	v_pk_mul_f32 v[34:35], v[42:43], v[46:47]
	v_mov_b32_e32 v38, v36
	v_fma_f32 v12, v39, v51, v34
	v_add_f32_e32 v12, v12, v35
	v_mul_f32_e32 v16, 0xbfb8aa3b, v12
	v_exp_f32_e32 v16, v16
	v_lshlrev_b32_e32 v34, 16, v17
	v_lshlrev_b32_e32 v35, 16, v13
	v_mov_b32_e32 v39, v44
	v_add_f32_e32 v16, 1.0, v16
	v_rcp_f32_e32 v16, v16
	v_pk_mul_f32 v[34:35], v[38:39], v[34:35]
	v_and_b32_e32 v13, 0xffff0000, v13
	v_mov_b32_e32 v44, v37
	v_mul_f32_e32 v42, v12, v16
	v_fma_f32 v12, v40, v52, v34
	v_add_f32_e32 v12, v12, v35
	v_mul_f32_e32 v16, 0xbfb8aa3b, v12
	v_exp_f32_e32 v16, v16
	s_nop 0
	v_add_f32_e32 v16, 1.0, v16
	v_rcp_f32_e32 v16, v16
	s_nop 0
	v_mul_f32_e32 v34, v12, v16
	v_and_b32_e32 v12, 0xffff0000, v17
	v_pk_mul_f32 v[12:13], v[44:45], v[12:13]
	v_mov_b32_e32 v16, v20
	v_fma_f32 v12, v41, v53, v12
	v_add_f32_e32 v12, v12, v13
	v_mul_f32_e32 v13, 0xbfb8aa3b, v12
	v_exp_f32_e32 v13, v13
	v_mov_b32_e32 v17, v28
	v_mov_b32_e32 v28, v21
	v_and_b32_e32 v21, s0, v3
	v_add_f32_e32 v13, 1.0, v13
	v_rcp_f32_e32 v13, v13
	s_mov_b32 s0, 0x3b800000
	s_mov_b32 s1, 0x3b000000
	v_mul_f32_e32 v35, v12, v13
	v_lshlrev_b32_e32 v13, 16, v14
	v_lshlrev_b32_e32 v12, 16, v18
	v_pk_mul_f32 v[12:13], v[16:17], v[12:13]
	v_mov_b32_e32 v16, v22
	v_fma_f32 v12, v24, v54, v12
	v_add_f32_e32 v12, v12, v13
	v_mul_f32_e32 v13, 0xbfb8aa3b, v12
	v_exp_f32_e32 v13, v13
	v_mov_b32_e32 v17, v30
	v_mov_b32_e32 v30, v23
	v_lshlrev_b32_e32 v23, 16, v2
	v_add_f32_e32 v13, 1.0, v13
	v_rcp_f32_e32 v13, v13
	v_and_b32_e32 v24, 0xffff0000, v3
	v_mul_f32_e32 v20, v12, v13
	v_and_b32_e32 v13, 0xffff0000, v14
	v_and_b32_e32 v12, 0xffff0000, v18
	v_pk_mul_f32 v[12:13], v[28:29], v[12:13]
	v_and_b32_e32 v18, 0xffff0000, v1
	v_fma_f32 v12, v25, v55, v12
	v_add_f32_e32 v12, v12, v13
	v_mul_f32_e32 v13, 0xbfb8aa3b, v12
	v_exp_f32_e32 v13, v13
	v_xor_b32_e32 v28, 4, v238
	v_lshlrev_b32_e32 v25, 16, v3
	v_add_f32_e32 v13, 1.0, v13
	v_rcp_f32_e32 v13, v13
	s_nop 0
	v_mul_f32_e32 v14, v12, v13
	v_lshlrev_b32_e32 v12, 16, v19
	v_lshlrev_b32_e32 v13, 16, v15
	v_pk_mul_f32 v[12:13], v[16:17], v[12:13]
	s_nop 0
	v_fma_f32 v12, v26, v105, v12
	v_add_f32_e32 v12, v12, v13
	v_mul_f32_e32 v13, 0xbfb8aa3b, v12
	v_exp_f32_e32 v13, v13
	s_nop 0
	v_add_f32_e32 v13, 1.0, v13
	v_rcp_f32_e32 v13, v13
	s_nop 0
	v_mul_f32_e32 v16, v12, v13
	v_and_b32_e32 v13, 0xffff0000, v15
	v_and_b32_e32 v12, 0xffff0000, v19
	v_pk_mul_f32 v[12:13], v[30:31], v[12:13]
	v_lshlrev_b32_e32 v19, 16, v1
	v_fma_f32 v12, v27, v112, v12
	v_add_f32_e32 v12, v12, v13
	v_mul_f32_e32 v13, 0xbfb8aa3b, v12
	v_exp_f32_e32 v13, v13
	s_nop 0
	v_add_f32_e32 v13, 1.0, v13
	v_rcp_f32_e32 v13, v13
	s_nop 0
	v_mul_f32_e32 v15, v12, v13
	v_cvt_pk_bf16_f32 v12, v48, v42
	v_cvt_pk_bf16_f32 v13, v34, v35
	v_cvt_pk_bf16_f32 v14, v20, v14
	v_cvt_pk_bf16_f32 v15, v16, v15
	flat_store_dwordx4 v[32:33], v[12:15] offset:16
	v_and_b32_e32 v20, 0xffff0000, v2
	v_mov_b32_e32 v22, v20
	v_lshlrev_b32_e32 v13, 16, v110
	v_lshlrev_b32_e32 v12, 16, v108
	v_mov_b32_e32 v14, v4
	v_mov_b32_e32 v15, v8
	v_pk_mul_f32 v[14:15], v[14:15], v[12:13]
	v_pk_mul_f32 v[26:27], v[20:21], v[20:21]
	v_sub_f32_e32 v14, v14, v15
	v_mul_f32_e32 v16, v61, v14
	v_mov_b32_e32 v14, v8
	v_mov_b32_e32 v15, v4
	v_pk_mul_f32 v[12:13], v[14:15], v[12:13]
	v_mov_b32_e32 v8, v5
	v_add_f32_e32 v4, v12, v13
	v_and_b32_e32 v13, 0xffff0000, v110
	v_and_b32_e32 v12, 0xffff0000, v108
	v_pk_mul_f32 v[14:15], v[8:9], v[12:13]
	v_mul_f32_e32 v17, v61, v4
	v_sub_f32_e32 v4, v14, v15
	v_mul_f32_e32 v14, v61, v4
	v_mov_b32_e32 v4, v9
	v_pk_mul_f32 v[4:5], v[4:5], v[12:13]
	v_mov_b32_e32 v8, v6
	v_add_f32_e32 v4, v4, v5
	v_mul_f32_e32 v12, v61, v4
	v_lshlrev_b32_e32 v5, 16, v111
	v_lshlrev_b32_e32 v4, 16, v109
	v_mov_b32_e32 v9, v10
	v_pk_mul_f32 v[8:9], v[8:9], v[4:5]
	v_xor_b32_e32 v21, 32, v238
	v_sub_f32_e32 v8, v8, v9
	v_mul_f32_e32 v13, v61, v8
	v_mov_b32_e32 v8, v10
	v_mov_b32_e32 v9, v6
	v_pk_mul_f32 v[4:5], v[8:9], v[4:5]
	v_mov_b32_e32 v10, v7
	v_add_f32_e32 v4, v4, v5
	v_mul_f32_e32 v15, v61, v4
	v_and_b32_e32 v5, 0xffff0000, v111
	v_and_b32_e32 v4, 0xffff0000, v109
	v_pk_mul_f32 v[8:9], v[10:11], v[4:5]
	v_xor_b32_e32 v27, 8, v238
	v_sub_f32_e32 v6, v8, v9
	v_mul_f32_e32 v8, v61, v6
	v_mov_b32_e32 v6, v11
	v_pk_mul_f32 v[4:5], v[6:7], v[4:5]
	v_mov_b32_e32 v29, v26
	v_add_f32_e32 v4, v4, v5
	v_mul_f32_e32 v7, v61, v4
	v_cvt_pk_bf16_f32 v4, v16, v14
	v_cvt_pk_bf16_f32 v5, v13, v8
	v_cvt_pk_bf16_f32 v6, v17, v12
	v_cvt_pk_bf16_f32 v7, v15, v7
	v_lshlrev_b64 v[14:15], 10, v[56:57]
	v_lshl_add_u64 v[10:11], v[82:83], 0, v[14:15]
	v_lshlrev_b32_e32 v16, 16, v0
	v_and_b32_e32 v17, 0xffff0000, v0
	flat_store_dwordx2 v[10:11], v[4:5]
	flat_store_dwordx2 v[10:11], v[6:7] offset:64
	v_pk_mul_f32 v[6:7], v[16:17], v[16:17]
	v_pk_mul_f32 v[0:1], v[18:19], v[18:19]
	v_add_f32_e32 v2, v6, v7
	v_add_f32_e32 v1, v1, v2
	v_add_f32_e32 v0, v0, v1
	v_pk_fma_f32 v[0:1], v[22:23], v[22:23], v[0:1] op_sel_hi:[1,1,0]
	v_xor_b32_e32 v22, 16, v238
	v_and_b32_e32 v0, 64, v238
	v_add_u32_e32 v0, 64, v0
	v_cmp_lt_i32_e32 vcc, v21, v0
	v_lshlrev_b32_e32 v12, 16, v106
	v_and_b32_e32 v13, 0xffff0000, v106
	v_cndmask_b32_e32 v21, v238, v21, vcc
	v_cmp_lt_i32_e32 vcc, v22, v0
	v_and_b32_e32 v10, 0xffff0000, v107
	v_lshlrev_b32_e32 v11, 16, v107
	v_cndmask_b32_e32 v22, v238, v22, vcc
	v_cmp_lt_i32_e32 vcc, v27, v0
	v_pk_mul_f32 v[6:7], v[12:13], v[12:13]
	v_pk_mul_f32 v[4:5], v[10:11], v[10:11]
	v_cndmask_b32_e32 v27, v238, v27, vcc
	v_cmp_lt_i32_e32 vcc, v28, v0
	v_pk_mul_f32 v[2:3], v[24:25], v[24:25]
	v_lshlrev_b32_e32 v21, 2, v21
	v_cndmask_b32_e32 v28, v238, v28, vcc
	v_lshlrev_b32_e32 v30, 2, v28
	v_xor_b32_e32 v28, 2, v238
	v_cmp_lt_i32_e32 vcc, v28, v0
	v_lshlrev_b32_e32 v22, 2, v22
	v_lshlrev_b32_e32 v27, 2, v27
	v_cndmask_b32_e32 v28, v238, v28, vcc
	v_lshlrev_b32_e32 v31, 2, v28
	v_xor_b32_e32 v28, 1, v238
	v_cmp_lt_i32_e32 vcc, v28, v0
	v_lshlrev_b64 v[8:9], 9, v[56:57]
	s_nop 0
	v_cndmask_b32_e32 v0, v238, v28, vcc
	v_lshlrev_b32_e32 v32, 2, v0
	v_mov_b32_e32 v28, v6
	v_mov_b32_e32 v0, v7
	v_pk_add_f32 v[0:1], v[28:29], v[0:1]
	v_mov_b32_e32 v6, v5
	v_mov_b32_e32 v7, v3
	v_pk_add_f32 v[0:1], v[6:7], v[0:1]
	v_mov_b32_e32 v5, v2
	v_pk_add_f32 v[0:1], v[4:5], v[0:1]
	ds_bpermute_b32 v3, v21, v1
	ds_bpermute_b32 v2, v21, v0
	s_waitcnt lgkmcnt(0)
; __device__ __forceinline__ unsigned cvt_pk_bf16(float lo, float hi) { unsigned r; asm volatile("v_cvt_pk_bf16_f32 %0, %1, %2" : "=v"(r) : "v"(lo), "v"(hi)); return r; }
; __device__ __forceinline__ float bf2f(bf16_t b) { return __uint_as_float(((unsigned)b) << 16); }
; __device__ __forceinline__ float bflo(unsigned w) { return __uint_as_float(w << 16); }
; __device__ __forceinline__ float bfhi(unsigned w) { return __uint_as_float(w & 0xffff0000u); }
; __device__ __forceinline__ void unpack8(u32x4 w, float* f) { f[0] = bflo(w.x); f[1] = bfhi(w.x); f[2] = bflo(w.y); f[3] = bfhi(w.y); f[4] = bflo(w.z); f[5] = bfhi(w.z); f[6] = bflo(w.w); f[7] = bfhi(w.w); }
; __device__ __forceinline__ u32x4 pack8(const float* f) { u32x4 w; w.x = cvt_pk_bf16(f[0], f[1]); w.y = cvt_pk_bf16(f[2], f[3]); w.z = cvt_pk_bf16(f[4], f[5]); w.w = cvt_pk_bf16(f[6], f[7]); return w; }
; __device__ __forceinline__ void prep_phase(const Params& p, const Bufs& B, int l) {
;     ...
;         { float f[8]; unpack8(cqv, f); float g4[4] = {bflo(ckvv.x), bfhi(ckvv.x), bflo(ckvv.y), bfhi(ckvv.y)};
;             float ssq = 0.f, ssk = g4[0] * g4[0] + g4[1] * g4[1] + g4[2] * g4[2] + g4[3] * g4[3];
; #pragma unroll
;             for (int i = 0; i < 8; ++i) ssq += f[i] * f[i];
; #pragma unroll
;             for (int o = 32; o > 0; o >>= 1) { ssq += __shfl_xor(ssq, o); ssk += __shfl_xor(ssk, o); }
;             const float rstd = rsqrtf(ssq * (1.f / 512.f) + EPS_), rstk = rsqrtf(ssk * (1.f / 256.f) + EPS_);
; #pragma unroll
;             for (int i = 0; i < 8; ++i) f[i] = f[i] * rstd * gq[lane * 8 + i];
;             *(u32x4*)(B.CQN + (size_t)s * 512 + lane * 8) = pack8(f);
; #pragma unroll
;             for (int i = 0; i < 4; ++i) g4[i] = g4[i] * rstk * gkv[lane * 4 + i];
;             u32x2 o; o.x = cvt_pk_bf16(g4[0], g4[1]); o.y = cvt_pk_bf16(g4[2], g4[3]); *(u32x2*)(B.CKVN + (size_t)s * 256 + lane * 4) = o; }
;         if (lane < 32) { const float x1 = bf2f(kr1), x2 = bf2f(kr2);
;             const unsigned short w = (unsigned short)(__builtin_amdgcn_cvt_pk_fp8_f32(x1 * krc - x2 * krs, x2 * krc + x1 * krs, 0, false) & 0xffff);
; #pragma unroll
;             for (int h = 0; h < 8; ++h) *(unsigned short*)((unsigned char*)B.K + ((size_t)h * S_ + s) * 192 + 128 + 2 * lane) = w; }
	v_pk_add_f32 v[0:1], v[0:1], v[2:3]
	ds_bpermute_b32 v3, v22, v1
	ds_bpermute_b32 v2, v22, v0
	s_waitcnt lgkmcnt(0)
	v_pk_add_f32 v[0:1], v[0:1], v[2:3]
	ds_bpermute_b32 v3, v27, v1
	ds_bpermute_b32 v2, v27, v0
	s_waitcnt lgkmcnt(0)
	v_pk_add_f32 v[0:1], v[0:1], v[2:3]
	ds_bpermute_b32 v3, v30, v1
	ds_bpermute_b32 v2, v30, v0
	s_waitcnt lgkmcnt(0)
	v_pk_add_f32 v[0:1], v[0:1], v[2:3]
	ds_bpermute_b32 v3, v31, v1
	ds_bpermute_b32 v2, v31, v0
	s_waitcnt lgkmcnt(0)
	v_pk_add_f32 v[0:1], v[0:1], v[2:3]
	ds_bpermute_b32 v3, v32, v1
	ds_bpermute_b32 v2, v32, v0
	s_waitcnt lgkmcnt(0)
	v_pk_add_f32 v[0:1], v[0:1], v[2:3]
	s_nop 0
	v_pk_fma_f32 v[0:1], v[0:1], s[0:1], v[242:243] op_sel_hi:[1,1,0]
	s_mov_b32 s0, 0x800000
	v_mul_f32_e32 v2, 0x4b800000, v1
	v_cmp_gt_f32_e32 vcc, s0, v0
	v_cmp_gt_f32_e64 s[0:1], s0, v1
	s_nop 1
	v_cndmask_b32_e64 v1, v1, v2, s[0:1]
	v_rsq_f32_e32 v1, v1
	s_nop 0
	v_mul_f32_e32 v2, 0x45800000, v1
	v_cndmask_b32_e64 v21, v1, v2, s[0:1]
	v_mul_f32_e32 v21, 0x3f553b94, v21
	v_mul_f32_e32 v1, 0x4b800000, v0
	v_cndmask_b32_e32 v0, v0, v1, vcc
	v_rsq_f32_e32 v22, v0
	global_load_dwordx4 v[0:3], v[70:71], off offset:16
	global_load_dwordx4 v[4:7], v[70:71], off
	v_mul_f32_e32 v16, v21, v16
	v_mul_f32_e32 v26, 0x45800000, v22
	s_waitcnt vmcnt(0)
	v_mul_f32_e32 v4, v4, v16
	v_mul_f32_e32 v16, v21, v17
	v_mul_f32_e32 v5, v5, v16
	v_mul_f32_e32 v16, v21, v19
	v_mul_f32_e32 v6, v6, v16
	v_mul_f32_e32 v16, v21, v18
	v_mul_f32_e32 v7, v7, v16
	v_mul_f32_e32 v16, v21, v23
	v_mul_f32_e32 v16, v0, v16
	v_mul_f32_e32 v0, v21, v20
	v_mul_f32_e32 v17, v1, v0
	v_mul_f32_e32 v0, v21, v25
	v_mul_f32_e32 v18, v2, v0
	v_mul_f32_e32 v0, v21, v24
	v_mul_f32_e32 v3, v3, v0
	v_cvt_pk_bf16_f32 v0, v4, v5
	v_lshl_add_u64 v[4:5], v[84:85], 0, v[14:15]
	v_cvt_pk_bf16_f32 v1, v6, v7
	v_cvt_pk_bf16_f32 v2, v16, v17
	v_cvt_pk_bf16_f32 v3, v18, v3
	flat_store_dwordx4 v[4:5], v[0:3]
	global_load_dwordx4 v[0:3], v[72:73], off
	v_cndmask_b32_e32 v19, v22, v26, vcc
	v_mul_f32_e32 v4, v19, v12
	s_waitcnt vmcnt(0)
	v_mul_f32_e32 v0, v4, v0
	v_mul_f32_e32 v4, v19, v13
	v_mul_f32_e32 v1, v4, v1
	v_mul_f32_e32 v4, v19, v11
	v_mul_f32_e32 v2, v4, v2
	v_mul_f32_e32 v4, v19, v10
	v_mul_f32_e32 v3, v4, v3
	v_cvt_pk_bf16_f32 v0, v0, v1
	v_cvt_pk_bf16_f32 v1, v2, v3
	v_lshl_add_u64 v[2:3], v[86:87], 0, v[8:9]
	flat_store_dwordx2 v[2:3], v[0:1]
	s_and_saveexec_b64 s[0:1], s[4:5]
	s_cbranch_execz .LBB0_498
	v_lshlrev_b32_e32 v1, 16, v99
	v_lshlrev_b32_e32 v0, 16, v97
	v_mul_f32_e32 v2, v103, v1
	v_mul_f32_e32 v1, v101, v1
	v_readlane_b32 s14, v254, 27
	v_fma_f32 v2, v101, v0, -v2
	v_fmac_f32_e32 v1, v103, v0
	v_mov_b32_e32 v4, v195
	v_readlane_b32 s15, v254, 28
	v_cvt_pk_fp8_f32 v4, v2, v1
	s_nop 0
	v_mov_b64_e32 v[0:1], s[14:15]
	s_movk_i32 s14, 0xc0
	v_mad_i64_i32 v[0:1], s[14:15], v56, s14, v[0:1]
	v_lshl_add_u64 v[0:1], v[0:1], 0, v[64:65]
	v_add_co_u32_e32 v2, vcc, 0x180000, v0
	flat_store_short v[0:1], v4 offset:128
	s_nop 0
	v_addc_co_u32_e32 v3, vcc, 0, v1, vcc
	flat_store_short v[2:3], v4 offset:128
	v_add_co_u32_e32 v2, vcc, 0x300000, v0
	s_nop 1
	v_addc_co_u32_e32 v3, vcc, 0, v1, vcc
	flat_store_short v[2:3], v4 offset:128
	v_add_co_u32_e32 v2, vcc, 0x480000, v0
	s_nop 1
	v_addc_co_u32_e32 v3, vcc, 0, v1, vcc
	flat_store_short v[2:3], v4 offset:128
	v_add_co_u32_e32 v2, vcc, 0x600000, v0
	s_nop 1
	v_addc_co_u32_e32 v3, vcc, 0, v1, vcc
	flat_store_short v[2:3], v4 offset:128
	v_add_co_u32_e32 v2, vcc, 0x780000, v0
	s_nop 1
	v_addc_co_u32_e32 v3, vcc, 0, v1, vcc
	flat_store_short v[2:3], v4 offset:128
	v_add_co_u32_e32 v2, vcc, 0x900000, v0
	s_nop 1
	v_addc_co_u32_e32 v3, vcc, 0, v1, vcc
	v_add_co_u32_e32 v0, vcc, 0xa80000, v0
	flat_store_short v[2:3], v4 offset:128
	s_nop 0
	v_addc_co_u32_e32 v1, vcc, 0, v1, vcc
	flat_store_short v[0:1], v4 offset:128
